# prologue: all four tiles of a pass keep their element+scale loads in flight (deferred LDS writes), on top of per-tile batching
# baseline (speedup 1.0000x reference)
.LBB0_10:
	s_mov_b32 s90, 0
	s_mul_i32 s7, s42, 0xade304d5
	s_mul_hi_u32 s8, s43, 0xade304d5
	s_mul_hi_u32 s6, s42, 0xade304d5
	s_add_u32 s7, s7, s8
	s_mul_i32 s5, s43, 0x4d4873ec
	s_addc_u32 s6, s6, 0
	s_mul_hi_u32 s4, s43, 0x4d4873ec
	s_add_u32 s5, s5, s7
	s_addc_u32 s4, s4, 0
	s_add_u32 s4, s6, s4
	s_addc_u32 s5, 0, 0
	s_mul_i32 s7, s42, 0x4d4873ec
	s_mul_hi_u32 s6, s42, 0x4d4873ec
	s_add_u32 s4, s7, s4
	s_addc_u32 s5, s6, s5
	s_ashr_i32 s6, s42, 31
	s_mul_i32 s7, s6, 0x4d4873ec
	s_mul_hi_u32 s8, s6, 0xade304d5
	s_add_i32 s7, s8, s7
	s_mul_i32 s6, s6, 0xade304d5
	s_add_i32 s7, s7, s6
	s_add_u32 s4, s4, s6
	s_addc_u32 s5, s5, s7
	s_ashr_i64 s[6:7], s[4:5], 11
	s_lshr_b32 s4, s5, 31
	s_add_u32 s4, s6, s4
	s_mulk_i32 s4, 0x1a80
	s_sub_i32 s4, s43, s4
	s_sext_i32_i16 s5, s4
	s_mulk_i32 s5, 0x4d49
	s_lshr_b32 s6, s5, 31
	s_ashr_i32 s5, s5, 26
	s_add_i32 s12, s5, s6
	s_mul_i32 s5, s12, 0xd40
	s_sub_i32 s4, s4, s5
	s_sext_i32_i16 s60, s4
	s_cmpk_gt_i32 s60, 0x63f
	s_cselect_b64 s[14:15], -1, 0
	s_mov_b64 s[6:7], -1
	s_and_b64 vcc, exec, s[14:15]
	s_cbranch_vccz .LBB0_19
	s_and_b32 s5, s60, 0xffff
	s_cmpk_gt_u32 s5, 0xa3f
	s_mov_b64 s[16:17], -1
	s_cbranch_scc0 .LBB0_17
	s_cmpk_gt_u32 s5, 0xc3f
	s_cbranch_scc0 .LBB0_14
	s_lshl_b32 s4, s60, 2
	s_add_i32 s4, s4, 0x7fffcf00
	s_lshl_b32 s5, s60, 6
	s_ashr_i32 s13, s12, 31
	s_and_b32 s4, s4, 0x7fffffc0
	s_and_b32 s20, s5, 0x3c0
	s_lshl_b64 s[6:7], s[12:13], 22
	s_add_u32 s22, s76, s6
	s_addc_u32 s23, s77, s7
	s_mov_b64 s[6:7], 0

.Lpro_c0:
	s_add_u32 s8, s43, 61
	s_addc_u32 s4, s42, 0
	s_mul_i32 s13, s4, 0xade304d5
	s_mul_hi_u32 s18, s8, 0xade304d5
	s_mul_hi_u32 s7, s4, 0xade304d5
	s_add_u32 s13, s13, s18
	s_mul_i32 s6, s8, 0x4d4873ec
	s_addc_u32 s7, s7, 0
	s_mul_hi_u32 s5, s8, 0x4d4873ec
	s_add_u32 s6, s6, s13
	s_addc_u32 s5, s5, 0
	s_add_u32 s5, s7, s5
	s_addc_u32 s6, 0, 0
	s_mul_i32 s13, s4, 0x4d4873ec
	s_mul_hi_u32 s7, s4, 0x4d4873ec
	s_add_u32 s5, s13, s5
	s_addc_u32 s6, s7, s6
	s_ashr_i32 s4, s4, 31
	s_mul_i32 s7, s4, 0x4d4873ec
	s_mul_hi_u32 s13, s4, 0xade304d5
	s_add_i32 s7, s13, s7
	s_mul_i32 s4, s4, 0xade304d5
	s_add_i32 s7, s7, s4
	s_add_u32 s4, s5, s4
	s_addc_u32 s5, s6, s7
	s_ashr_i64 s[6:7], s[4:5], 11
	s_lshr_b32 s4, s5, 31
	s_add_u32 s4, s6, s4
	s_mulk_i32 s4, 0x1a80
	s_sub_i32 s5, s8, s4
	s_sext_i32_i16 s4, s5
	s_mulk_i32 s4, 0x4d49
	s_lshr_b32 s6, s4, 31
	s_ashr_i32 s4, s4, 26
	s_add_i32 s4, s4, s6
	s_mul_i32 s6, s4, 0xd40
	s_sub_i32 s5, s5, s6
	s_sext_i32_i16 s7, s5
	s_cmpk_lt_i32 s7, 0x640
	s_mov_b64 s[26:27], -1
	s_cbranch_scc1 .LBB0_120
	s_and_b32 s5, s7, 0xffff
	s_cmpk_lt_u32 s5, 0xa40
	s_mov_b64 s[18:19], -1
	s_cbranch_scc1 .LBB0_118
	s_cmpk_lt_u32 s5, 0xc40
	s_cbranch_scc1 .LBB0_115
	s_lshl_b32 s5, s7, 2
	s_add_i32 s5, s5, 0x7fffcf00
	s_and_b32 s6, s5, 0x7fffffc0
	s_lshl_b32 s5, s7, 6
	s_and_b32 s22, s5, 0x3c0
	s_ashr_i32 s5, s4, 31
	s_lshl_b64 s[18:19], s[4:5], 22
	s_add_u32 s24, s76, s18
	s_addc_u32 s25, s77, s19
	s_mov_b64 s[18:19], 0

.Lpro_c1:
	s_add_u32 s8, s43, 0x7a
	s_addc_u32 s4, s42, 0
	s_mul_i32 s13, s4, 0xade304d5
	s_mul_hi_u32 s18, s8, 0xade304d5
	s_mul_hi_u32 s7, s4, 0xade304d5
	s_add_u32 s13, s13, s18
	s_mul_i32 s6, s8, 0x4d4873ec
	s_addc_u32 s7, s7, 0
	s_mul_hi_u32 s5, s8, 0x4d4873ec
	s_add_u32 s6, s6, s13
	s_addc_u32 s5, s5, 0
	s_add_u32 s5, s7, s5
	s_addc_u32 s6, 0, 0
	s_mul_i32 s13, s4, 0x4d4873ec
	s_mul_hi_u32 s7, s4, 0x4d4873ec
	s_add_u32 s5, s13, s5
	s_addc_u32 s6, s7, s6
	s_ashr_i32 s4, s4, 31
	s_mul_i32 s7, s4, 0x4d4873ec
	s_mul_hi_u32 s13, s4, 0xade304d5
	s_add_i32 s7, s13, s7
	s_mul_i32 s4, s4, 0xade304d5
	s_add_i32 s7, s7, s4
	s_add_u32 s4, s5, s4
	s_addc_u32 s5, s6, s7
	s_ashr_i64 s[6:7], s[4:5], 11
	s_lshr_b32 s4, s5, 31
	s_add_u32 s4, s6, s4
	s_mulk_i32 s4, 0x1a80
	s_sub_i32 s5, s8, s4
	s_sext_i32_i16 s4, s5
	s_mulk_i32 s4, 0x4d49
	s_lshr_b32 s6, s4, 31
	s_ashr_i32 s4, s4, 26
	s_add_i32 s4, s4, s6
	s_mul_i32 s6, s4, 0xd40
	s_sub_i32 s5, s5, s6
	s_sext_i32_i16 s7, s5
	s_cmpk_lt_i32 s7, 0x640
	s_mov_b64 s[26:27], -1
	s_cbranch_scc1 .LBB0_221
	s_and_b32 s5, s7, 0xffff
	s_cmpk_lt_u32 s5, 0xa40
	s_mov_b64 s[18:19], -1
	s_cbranch_scc1 .LBB0_219
	s_cmpk_lt_u32 s5, 0xc40
	s_cbranch_scc1 .LBB0_216
	s_lshl_b32 s5, s7, 2
	s_add_i32 s5, s5, 0x7fffcf00
	s_and_b32 s6, s5, 0x7fffffc0
	s_lshl_b32 s5, s7, 6
	s_and_b32 s22, s5, 0x3c0
	s_ashr_i32 s5, s4, 31
	s_lshl_b64 s[18:19], s[4:5], 22
	s_add_u32 s24, s76, s18
	s_addc_u32 s25, s77, s19
	s_mov_b64 s[18:19], 0

.Lpro_c2:
	s_add_u32 s8, s43, 0xb7
	s_addc_u32 s4, s42, 0
	s_mul_i32 s13, s4, 0xade304d5
	s_mul_hi_u32 s18, s8, 0xade304d5
	s_mul_hi_u32 s7, s4, 0xade304d5
	s_add_u32 s13, s13, s18
	s_mul_i32 s6, s8, 0x4d4873ec
	s_addc_u32 s7, s7, 0
	s_mul_hi_u32 s5, s8, 0x4d4873ec
	s_add_u32 s6, s6, s13
	s_addc_u32 s5, s5, 0
	s_add_u32 s5, s7, s5
	s_addc_u32 s6, 0, 0
	s_mul_i32 s13, s4, 0x4d4873ec
	s_mul_hi_u32 s7, s4, 0x4d4873ec
	s_add_u32 s5, s13, s5
	s_addc_u32 s6, s7, s6
	s_ashr_i32 s4, s4, 31
	s_mul_i32 s7, s4, 0x4d4873ec
	s_mul_hi_u32 s13, s4, 0xade304d5
	s_add_i32 s7, s13, s7
	s_mul_i32 s4, s4, 0xade304d5
	s_add_i32 s7, s7, s4
	s_add_u32 s4, s5, s4
	s_addc_u32 s5, s6, s7
	s_ashr_i64 s[6:7], s[4:5], 11
	s_lshr_b32 s4, s5, 31
	s_add_u32 s4, s6, s4
	s_mulk_i32 s4, 0x1a80
	s_sub_i32 s5, s8, s4
	s_sext_i32_i16 s4, s5
	s_mulk_i32 s4, 0x4d49
	s_lshr_b32 s6, s4, 31
	s_ashr_i32 s4, s4, 26
	s_add_i32 s4, s4, s6
	s_mul_i32 s6, s4, 0xd40
	s_sub_i32 s5, s5, s6
	s_sext_i32_i16 s7, s5
	s_cmpk_lt_i32 s7, 0x640
	s_mov_b64 s[26:27], -1
	s_cbranch_scc1 .LBB0_322
	s_and_b32 s5, s7, 0xffff
	s_cmpk_lt_u32 s5, 0xa40
	s_mov_b64 s[18:19], -1
	s_cbranch_scc1 .LBB0_320
	s_cmpk_lt_u32 s5, 0xc40
	s_cbranch_scc1 .LBB0_317
	s_lshl_b32 s5, s7, 2
	s_add_i32 s5, s5, 0x7fffcf00
	s_and_b32 s6, s5, 0x7fffffc0
	s_lshl_b32 s5, s7, 6
	s_and_b32 s22, s5, 0x3c0
	s_ashr_i32 s5, s4, 31
	s_lshl_b64 s[18:19], s[4:5], 22
	s_add_u32 s24, s76, s18
	s_addc_u32 s25, s77, s19
	s_mov_b64 s[18:19], 0

.LBB0_414:
	s_cmp_eq_u32 s90, 0
	s_cbranch_scc1 .Lpro_fl_done
	s_waitcnt vmcnt(0)
	s_bitcmp1_b32 s90, 0
	s_cbranch_scc0 .Lpro_fl_n0
	s_bitcmp1_b32 s90, 4
	s_cbranch_scc0 .Lpro_fl_w0
	v_mul_f32_e32 v64, v64, v72
	v_mul_f32_e32 v65, v65, v73
	v_mul_f32_e32 v66, v66, v74
	v_mul_f32_e32 v67, v67, v75
	v_mul_f32_e32 v68, v68, v76
	v_mul_f32_e32 v69, v69, v77
	v_mul_f32_e32 v70, v70, v78
	v_mul_f32_e32 v71, v71, v79
.Lpro_fl_w0:
	ds_write_b32 v19, v64
	ds_write_b32 v19, v65 offset:260
	ds_write_b32 v19, v66 offset:520
	ds_write_b32 v19, v67 offset:780
	ds_write_b32 v19, v68 offset:1040
	ds_write_b32 v19, v69 offset:1300
	ds_write_b32 v19, v70 offset:1560
	ds_write_b32 v20, v71
.Lpro_fl_n0:
	s_bitcmp1_b32 s90, 1
	s_cbranch_scc0 .Lpro_fl_n1
	s_bitcmp1_b32 s90, 5
	s_cbranch_scc0 .Lpro_fl_w1
	v_mul_f32_e32 v80, v80, v88
	v_mul_f32_e32 v81, v81, v89
	v_mul_f32_e32 v82, v82, v90
	v_mul_f32_e32 v83, v83, v91
	v_mul_f32_e32 v84, v84, v92
	v_mul_f32_e32 v85, v85, v93
	v_mul_f32_e32 v86, v86, v94
	v_mul_f32_e32 v87, v87, v95
.Lpro_fl_w1:
	ds_write_b32 v19, v80 offset:16896
	ds_write_b32 v19, v81 offset:17156
	ds_write_b32 v19, v82 offset:17416
	ds_write_b32 v19, v83 offset:17676
	ds_write_b32 v19, v84 offset:17936
	ds_write_b32 v19, v85 offset:18196
	ds_write_b32 v19, v86 offset:18456
	ds_write_b32 v20, v87 offset:16896
.Lpro_fl_n1:
	s_bitcmp1_b32 s90, 2
	s_cbranch_scc0 .Lpro_fl_n2
	s_bitcmp1_b32 s90, 6
	s_cbranch_scc0 .Lpro_fl_w2
	v_mul_f32_e32 v96, v96, v104
	v_mul_f32_e32 v97, v97, v105
	v_mul_f32_e32 v98, v98, v106
	v_mul_f32_e32 v99, v99, v107
	v_mul_f32_e32 v100, v100, v108
	v_mul_f32_e32 v101, v101, v109
	v_mul_f32_e32 v102, v102, v110
	v_mul_f32_e32 v103, v103, v111
.Lpro_fl_w2:
	ds_write_b32 v19, v96 offset:33792
	ds_write_b32 v19, v97 offset:34052
	ds_write_b32 v19, v98 offset:34312
	ds_write_b32 v19, v99 offset:34572
	ds_write_b32 v19, v100 offset:34832
	ds_write_b32 v19, v101 offset:35092
	ds_write_b32 v19, v102 offset:35352
	ds_write_b32 v20, v103 offset:33792
.Lpro_fl_n2:
	s_bitcmp1_b32 s90, 3
	s_cbranch_scc0 .Lpro_fl_n3
	s_bitcmp1_b32 s90, 7
	s_cbranch_scc0 .Lpro_fl_w3
	v_mul_f32_e32 v112, v112, v120
	v_mul_f32_e32 v113, v113, v121
	v_mul_f32_e32 v114, v114, v122
	v_mul_f32_e32 v115, v115, v123
	v_mul_f32_e32 v116, v116, v124
	v_mul_f32_e32 v117, v117, v125
	v_mul_f32_e32 v118, v118, v126
	v_mul_f32_e32 v119, v119, v127
.Lpro_fl_w3:
	ds_write_b32 v19, v112 offset:50688
	ds_write_b32 v19, v113 offset:50948
	ds_write_b32 v19, v114 offset:51208
	ds_write_b32 v19, v115 offset:51468
	ds_write_b32 v19, v116 offset:51728
	ds_write_b32 v19, v117 offset:51988
	ds_write_b32 v19, v118 offset:52248
	ds_write_b32 v20, v119 offset:50688
.Lpro_fl_n3:
.Lpro_fl_done:
	s_waitcnt lgkmcnt(0)
	s_barrier
	s_mov_b64 s[18:19], -1
	s_and_b64 vcc, exec, s[14:15]
	s_cbranch_vccz .LBB0_424
	s_and_b32 s8, s60, 0xffff
	s_cmpk_gt_u32 s8, 0xa3f
	s_mov_b64 s[14:15], -1
	s_cbranch_scc0 .LBB0_421
	s_lshl_b32 s14, s60, 6
	s_ashr_i32 s13, s12, 31
	s_cmpk_gt_u32 s8, 0xc3f
	s_mov_b64 s[6:7], -1
	s_cbranch_scc0 .LBB0_418
	s_lshl_b32 s4, s60, 2
	s_add_i32 s4, s4, 0x7fffcf00
	s_and_b32 s20, s4, 0x7fffffc0
	s_and_b32 s8, s14, 0x3c0
	s_lshl_b64 s[4:5], s[12:13], 21
	s_add_u32 s4, s34, s4
	s_addc_u32 s5, s35, s5
	s_mov_b64 s[6:7], 0

.LBB0_465:
	s_lshl_b32 s26, s18, 2
	v_add_u32_e32 v9, s20, v2
	v_mul_lo_u32 v8, v9, s26
	v_add_u32_e32 v8, v8, v4
	global_load_dword v64, v8, s[4:5]
	v_add_u32_e32 v8, s26, v8
	global_load_dword v65, v8, s[4:5]
	v_add_u32_e32 v8, s26, v8
	global_load_dword v66, v8, s[4:5]
	v_add_u32_e32 v8, s26, v8
	global_load_dword v67, v8, s[4:5]
	v_add_u32_e32 v8, s26, v8
	global_load_dword v68, v8, s[4:5]
	v_add_u32_e32 v8, s26, v8
	global_load_dword v69, v8, s[4:5]
	v_add_u32_e32 v8, s26, v8
	global_load_dword v70, v8, s[4:5]
	v_add_u32_e32 v8, s26, v8
	global_load_dword v71, v8, s[4:5]
	s_bitset1_b32 s90, 0
	s_cmp_eq_u64 s[16:17], 0
	s_cbranch_scc1 .Lpro_ns0
	v_lshlrev_b32_e32 v9, 2, v9
	global_load_dwordx4 v[72:75], v9, s[16:17]
	global_load_dwordx4 v[76:79], v9, s[16:17] offset:16
	s_bitset1_b32 s90, 4
.Lpro_ns0:
	s_cmpk_lt_i32 s31, 0x1a7f
	s_cselect_b64 s[16:17], -1, 0
	s_cmpk_gt_i32 s31, 0x1a7e
	s_cbranch_scc1 .LBB0_414
	s_branch .Lpro_c0

.LBB0_473:
	s_lshl_b32 s28, s20, 2
	v_add_u32_e32 v9, s22, v2
	v_mul_lo_u32 v8, v9, s28
	v_add_u32_e32 v8, v8, v4
	global_load_dword v80, v8, s[6:7]
	v_add_u32_e32 v8, s28, v8
	global_load_dword v81, v8, s[6:7]
	v_add_u32_e32 v8, s28, v8
	global_load_dword v82, v8, s[6:7]
	v_add_u32_e32 v8, s28, v8
	global_load_dword v83, v8, s[6:7]
	v_add_u32_e32 v8, s28, v8
	global_load_dword v84, v8, s[6:7]
	v_add_u32_e32 v8, s28, v8
	global_load_dword v85, v8, s[6:7]
	v_add_u32_e32 v8, s28, v8
	global_load_dword v86, v8, s[6:7]
	v_add_u32_e32 v8, s28, v8
	global_load_dword v87, v8, s[6:7]
	s_bitset1_b32 s90, 1
	s_cmp_eq_u64 s[18:19], 0
	s_cbranch_scc1 .Lpro_ns1
	v_lshlrev_b32_e32 v9, 2, v9
	global_load_dwordx4 v[88:91], v9, s[18:19]
	global_load_dwordx4 v[92:95], v9, s[18:19] offset:16
	s_bitset1_b32 s90, 5
.Lpro_ns1:
	s_add_i32 s4, s31, 2
	s_cmpk_gt_i32 s4, 0x1a7f
	s_cbranch_scc1 .LBB0_414
	s_branch .Lpro_c1

.LBB0_481:
	s_lshl_b32 s28, s20, 2
	v_add_u32_e32 v9, s22, v2
	v_mul_lo_u32 v8, v9, s28
	v_add_u32_e32 v8, v8, v4
	global_load_dword v96, v8, s[6:7]
	v_add_u32_e32 v8, s28, v8
	global_load_dword v97, v8, s[6:7]
	v_add_u32_e32 v8, s28, v8
	global_load_dword v98, v8, s[6:7]
	v_add_u32_e32 v8, s28, v8
	global_load_dword v99, v8, s[6:7]
	v_add_u32_e32 v8, s28, v8
	global_load_dword v100, v8, s[6:7]
	v_add_u32_e32 v8, s28, v8
	global_load_dword v101, v8, s[6:7]
	v_add_u32_e32 v8, s28, v8
	global_load_dword v102, v8, s[6:7]
	v_add_u32_e32 v8, s28, v8
	global_load_dword v103, v8, s[6:7]
	s_bitset1_b32 s90, 2
	s_cmp_eq_u64 s[18:19], 0
	s_cbranch_scc1 .Lpro_ns2
	v_lshlrev_b32_e32 v9, 2, v9
	global_load_dwordx4 v[104:107], v9, s[18:19]
	global_load_dwordx4 v[108:111], v9, s[18:19] offset:16
	s_bitset1_b32 s90, 6
.Lpro_ns2:
	s_add_i32 s4, s31, 3
	s_cmpk_gt_i32 s4, 0x1a7f
	s_cbranch_scc1 .LBB0_414
	s_branch .Lpro_c2

.LBB0_489:
	s_lshl_b32 s28, s20, 2
	v_add_u32_e32 v9, s22, v2
	v_mul_lo_u32 v8, v9, s28
	v_add_u32_e32 v8, v8, v4
	global_load_dword v112, v8, s[6:7]
	v_add_u32_e32 v8, s28, v8
	global_load_dword v113, v8, s[6:7]
	v_add_u32_e32 v8, s28, v8
	global_load_dword v114, v8, s[6:7]
	v_add_u32_e32 v8, s28, v8
	global_load_dword v115, v8, s[6:7]
	v_add_u32_e32 v8, s28, v8
	global_load_dword v116, v8, s[6:7]
	v_add_u32_e32 v8, s28, v8
	global_load_dword v117, v8, s[6:7]
	v_add_u32_e32 v8, s28, v8
	global_load_dword v118, v8, s[6:7]
	v_add_u32_e32 v8, s28, v8
	global_load_dword v119, v8, s[6:7]
	s_bitset1_b32 s90, 3
	s_cmp_eq_u64 s[18:19], 0
	s_cbranch_scc1 .Lpro_ns3
	v_lshlrev_b32_e32 v9, 2, v9
	global_load_dwordx4 v[120:123], v9, s[18:19]
	global_load_dwordx4 v[124:127], v9, s[18:19] offset:16
	s_bitset1_b32 s90, 7
